# phase-0 modulation GEMV: k-loop fully unrolled with row loads issued 3 iterations ahead (was 16 exposed round trips per item)
# speedup vs baseline: 1.0278x; 1.0037x over previous
.LBB0_1106:
	v_mov_b32_e32 v142, v4
	v_mov_b32_e32 v143, v5
	s_mov_b64 s[10:11], 0x6000
	v_lshl_add_u64 v[144:145], v[142:143], 0, s[10:11]
	v_lshl_add_u64 v[146:147], v[144:145], 0, s[10:11]
	v_lshl_add_u64 v[148:149], v[146:147], 0, s[10:11]
	v_lshl_add_u64 v[150:151], v[148:149], 0, s[10:11]
	v_lshl_add_u64 v[152:153], v[150:151], 0, s[10:11]
	v_lshl_add_u64 v[154:155], v[152:153], 0, s[10:11]
	v_lshl_add_u64 v[156:157], v[154:155], 0, s[10:11]
	s_mov_b64 s[10:11], 0x30000
	global_load_dword v38, v[142:143], off
	global_load_dword v40, v[144:145], off
	global_load_dword v42, v[146:147], off
	global_load_dword v44, v[148:149], off
	global_load_dword v46, v[150:151], off
	global_load_dword v48, v[152:153], off
	global_load_dword v50, v[154:155], off
	global_load_dword v52, v[156:157], off
	v_lshl_add_u64 v[142:143], v[142:143], 0, s[10:11]
	v_lshl_add_u64 v[144:145], v[144:145], 0, s[10:11]
	v_lshl_add_u64 v[146:147], v[146:147], 0, s[10:11]
	v_lshl_add_u64 v[148:149], v[148:149], 0, s[10:11]
	v_lshl_add_u64 v[150:151], v[150:151], 0, s[10:11]
	v_lshl_add_u64 v[152:153], v[152:153], 0, s[10:11]
	v_lshl_add_u64 v[154:155], v[154:155], 0, s[10:11]
	v_lshl_add_u64 v[156:157], v[156:157], 0, s[10:11]
	global_load_dword v62, v[142:143], off
	global_load_dword v64, v[144:145], off
	global_load_dword v66, v[146:147], off
	global_load_dword v68, v[148:149], off
	global_load_dword v70, v[150:151], off
	global_load_dword v72, v[152:153], off
	global_load_dword v74, v[154:155], off
	global_load_dword v76, v[156:157], off
	v_lshl_add_u64 v[142:143], v[142:143], 0, s[10:11]
	v_lshl_add_u64 v[144:145], v[144:145], 0, s[10:11]
	v_lshl_add_u64 v[146:147], v[146:147], 0, s[10:11]
	v_lshl_add_u64 v[148:149], v[148:149], 0, s[10:11]
	v_lshl_add_u64 v[150:151], v[150:151], 0, s[10:11]
	v_lshl_add_u64 v[152:153], v[152:153], 0, s[10:11]
	v_lshl_add_u64 v[154:155], v[154:155], 0, s[10:11]
	v_lshl_add_u64 v[156:157], v[156:157], 0, s[10:11]
	global_load_dword v78, v[142:143], off
	global_load_dword v80, v[144:145], off
	global_load_dword v82, v[146:147], off
	global_load_dword v84, v[148:149], off
	global_load_dword v86, v[150:151], off
	global_load_dword v88, v[152:153], off
	global_load_dword v90, v[154:155], off
	global_load_dword v92, v[156:157], off
	v_lshl_add_u64 v[142:143], v[142:143], 0, s[10:11]
	v_lshl_add_u64 v[144:145], v[144:145], 0, s[10:11]
	v_lshl_add_u64 v[146:147], v[146:147], 0, s[10:11]
	v_lshl_add_u64 v[148:149], v[148:149], 0, s[10:11]
	v_lshl_add_u64 v[150:151], v[150:151], 0, s[10:11]
	v_lshl_add_u64 v[152:153], v[152:153], 0, s[10:11]
	v_lshl_add_u64 v[154:155], v[154:155], 0, s[10:11]
	v_lshl_add_u64 v[156:157], v[156:157], 0, s[10:11]
	global_load_dword v94, v[142:143], off
	global_load_dword v96, v[144:145], off
	global_load_dword v102, v[146:147], off
	global_load_dword v104, v[148:149], off
	global_load_dword v106, v[150:151], off
	global_load_dword v110, v[152:153], off
	global_load_dword v114, v[154:155], off
	global_load_dword v116, v[156:157], off
	v_lshl_add_u64 v[142:143], v[142:143], 0, s[10:11]
	v_lshl_add_u64 v[144:145], v[144:145], 0, s[10:11]
	v_lshl_add_u64 v[146:147], v[146:147], 0, s[10:11]
	v_lshl_add_u64 v[148:149], v[148:149], 0, s[10:11]
	v_lshl_add_u64 v[150:151], v[150:151], 0, s[10:11]
	v_lshl_add_u64 v[152:153], v[152:153], 0, s[10:11]
	v_lshl_add_u64 v[154:155], v[154:155], 0, s[10:11]
	v_lshl_add_u64 v[156:157], v[156:157], 0, s[10:11]
	ds_read_b128 v[14:17], v12
	ds_read_b128 v[18:21], v12 offset:16
	ds_read_b128 v[22:25], v12 offset:4096
	ds_read_b128 v[26:29], v12 offset:4112
	ds_read_b128 v[30:33], v12 offset:8192
	ds_read_b128 v[34:37], v12 offset:8208
	v_add_u32_e32 v12, 32, v12
	s_waitcnt lgkmcnt(3)
	v_mov_b32_e32 v55, v22
	s_waitcnt lgkmcnt(1)
	v_mov_b32_e32 v54, v30
	v_mov_b32_e32 v22, v31
	v_mov_b32_e32 v30, v32
	v_mov_b32_e32 v31, v24
	v_mov_b32_e32 v24, v33
	s_waitcnt lgkmcnt(0)
	v_mov_b32_e32 v32, v34
	v_mov_b32_e32 v33, v26
	v_mov_b32_e32 v26, v35
	v_mov_b32_e32 v34, v36
	v_mov_b32_e32 v35, v28
	v_mov_b32_e32 v28, v37
	s_waitcnt vmcnt(24)
	v_fmac_f32_e32 v11, v38, v14
	v_pk_fma_f32 v[6:7], v[38:39], v[54:55], v[6:7] op_sel_hi:[0,1,1]
	v_fmac_f32_e32 v11, v40, v15
	v_pk_fma_f32 v[6:7], v[40:41], v[22:23], v[6:7] op_sel_hi:[0,1,1]
	v_fmac_f32_e32 v11, v42, v16
	v_pk_fma_f32 v[6:7], v[42:43], v[30:31], v[6:7] op_sel_hi:[0,1,1]
	v_fmac_f32_e32 v11, v44, v17
	v_pk_fma_f32 v[6:7], v[44:45], v[24:25], v[6:7] op_sel_hi:[0,1,1]
	v_fmac_f32_e32 v11, v46, v18
	v_pk_fma_f32 v[6:7], v[46:47], v[32:33], v[6:7] op_sel_hi:[0,1,1]
	v_fmac_f32_e32 v11, v48, v19
	v_pk_fma_f32 v[6:7], v[48:49], v[26:27], v[6:7] op_sel_hi:[0,1,1]
	v_fmac_f32_e32 v11, v50, v20
	v_pk_fma_f32 v[6:7], v[50:51], v[34:35], v[6:7] op_sel_hi:[0,1,1]
	v_fmac_f32_e32 v11, v52, v21
	v_pk_fma_f32 v[6:7], v[52:53], v[28:29], v[6:7] op_sel_hi:[0,1,1]
	global_load_dword v38, v[142:143], off
	global_load_dword v40, v[144:145], off
	global_load_dword v42, v[146:147], off
	global_load_dword v44, v[148:149], off
	global_load_dword v46, v[150:151], off
	global_load_dword v48, v[152:153], off
	global_load_dword v50, v[154:155], off
	global_load_dword v52, v[156:157], off
	v_lshl_add_u64 v[142:143], v[142:143], 0, s[10:11]
	v_lshl_add_u64 v[144:145], v[144:145], 0, s[10:11]
	v_lshl_add_u64 v[146:147], v[146:147], 0, s[10:11]
	v_lshl_add_u64 v[148:149], v[148:149], 0, s[10:11]
	v_lshl_add_u64 v[150:151], v[150:151], 0, s[10:11]
	v_lshl_add_u64 v[152:153], v[152:153], 0, s[10:11]
	v_lshl_add_u64 v[154:155], v[154:155], 0, s[10:11]
	v_lshl_add_u64 v[156:157], v[156:157], 0, s[10:11]
	ds_read_b128 v[14:17], v12
	ds_read_b128 v[18:21], v12 offset:16
	ds_read_b128 v[22:25], v12 offset:4096
	ds_read_b128 v[26:29], v12 offset:4112
	ds_read_b128 v[30:33], v12 offset:8192
	ds_read_b128 v[34:37], v12 offset:8208
	v_add_u32_e32 v12, 32, v12
	s_waitcnt lgkmcnt(3)
	v_mov_b32_e32 v55, v22
	s_waitcnt lgkmcnt(1)
	v_mov_b32_e32 v54, v30
	v_mov_b32_e32 v22, v31
	v_mov_b32_e32 v30, v32
	v_mov_b32_e32 v31, v24
	v_mov_b32_e32 v24, v33
	s_waitcnt lgkmcnt(0)
	v_mov_b32_e32 v32, v34
	v_mov_b32_e32 v33, v26
	v_mov_b32_e32 v26, v35
	v_mov_b32_e32 v34, v36
	v_mov_b32_e32 v35, v28
	v_mov_b32_e32 v28, v37
	s_waitcnt vmcnt(24)
	v_fmac_f32_e32 v11, v62, v14
	v_pk_fma_f32 v[6:7], v[62:63], v[54:55], v[6:7] op_sel_hi:[0,1,1]
	v_fmac_f32_e32 v11, v64, v15
	v_pk_fma_f32 v[6:7], v[64:65], v[22:23], v[6:7] op_sel_hi:[0,1,1]
	v_fmac_f32_e32 v11, v66, v16
	v_pk_fma_f32 v[6:7], v[66:67], v[30:31], v[6:7] op_sel_hi:[0,1,1]
	v_fmac_f32_e32 v11, v68, v17
	v_pk_fma_f32 v[6:7], v[68:69], v[24:25], v[6:7] op_sel_hi:[0,1,1]
	v_fmac_f32_e32 v11, v70, v18
	v_pk_fma_f32 v[6:7], v[70:71], v[32:33], v[6:7] op_sel_hi:[0,1,1]
	v_fmac_f32_e32 v11, v72, v19
	v_pk_fma_f32 v[6:7], v[72:73], v[26:27], v[6:7] op_sel_hi:[0,1,1]
	v_fmac_f32_e32 v11, v74, v20
	v_pk_fma_f32 v[6:7], v[74:75], v[34:35], v[6:7] op_sel_hi:[0,1,1]
	v_fmac_f32_e32 v11, v76, v21
	v_pk_fma_f32 v[6:7], v[76:77], v[28:29], v[6:7] op_sel_hi:[0,1,1]
	global_load_dword v62, v[142:143], off
	global_load_dword v64, v[144:145], off
	global_load_dword v66, v[146:147], off
	global_load_dword v68, v[148:149], off
	global_load_dword v70, v[150:151], off
	global_load_dword v72, v[152:153], off
	global_load_dword v74, v[154:155], off
	global_load_dword v76, v[156:157], off
	v_lshl_add_u64 v[142:143], v[142:143], 0, s[10:11]
	v_lshl_add_u64 v[144:145], v[144:145], 0, s[10:11]
	v_lshl_add_u64 v[146:147], v[146:147], 0, s[10:11]
	v_lshl_add_u64 v[148:149], v[148:149], 0, s[10:11]
	v_lshl_add_u64 v[150:151], v[150:151], 0, s[10:11]
	v_lshl_add_u64 v[152:153], v[152:153], 0, s[10:11]
	v_lshl_add_u64 v[154:155], v[154:155], 0, s[10:11]
	v_lshl_add_u64 v[156:157], v[156:157], 0, s[10:11]
	ds_read_b128 v[14:17], v12
	ds_read_b128 v[18:21], v12 offset:16
	ds_read_b128 v[22:25], v12 offset:4096
	ds_read_b128 v[26:29], v12 offset:4112
	ds_read_b128 v[30:33], v12 offset:8192
	ds_read_b128 v[34:37], v12 offset:8208
	v_add_u32_e32 v12, 32, v12
	s_waitcnt lgkmcnt(3)
	v_mov_b32_e32 v55, v22
	s_waitcnt lgkmcnt(1)
	v_mov_b32_e32 v54, v30
	v_mov_b32_e32 v22, v31
	v_mov_b32_e32 v30, v32
	v_mov_b32_e32 v31, v24
	v_mov_b32_e32 v24, v33
	s_waitcnt lgkmcnt(0)
	v_mov_b32_e32 v32, v34
	v_mov_b32_e32 v33, v26
	v_mov_b32_e32 v26, v35
	v_mov_b32_e32 v34, v36
	v_mov_b32_e32 v35, v28
	v_mov_b32_e32 v28, v37
	s_waitcnt vmcnt(24)
	v_fmac_f32_e32 v11, v78, v14
	v_pk_fma_f32 v[6:7], v[78:79], v[54:55], v[6:7] op_sel_hi:[0,1,1]
	v_fmac_f32_e32 v11, v80, v15
	v_pk_fma_f32 v[6:7], v[80:81], v[22:23], v[6:7] op_sel_hi:[0,1,1]
	v_fmac_f32_e32 v11, v82, v16
	v_pk_fma_f32 v[6:7], v[82:83], v[30:31], v[6:7] op_sel_hi:[0,1,1]
	v_fmac_f32_e32 v11, v84, v17
	v_pk_fma_f32 v[6:7], v[84:85], v[24:25], v[6:7] op_sel_hi:[0,1,1]
	v_fmac_f32_e32 v11, v86, v18
	v_pk_fma_f32 v[6:7], v[86:87], v[32:33], v[6:7] op_sel_hi:[0,1,1]
	v_fmac_f32_e32 v11, v88, v19
	v_pk_fma_f32 v[6:7], v[88:89], v[26:27], v[6:7] op_sel_hi:[0,1,1]
	v_fmac_f32_e32 v11, v90, v20
	v_pk_fma_f32 v[6:7], v[90:91], v[34:35], v[6:7] op_sel_hi:[0,1,1]
	v_fmac_f32_e32 v11, v92, v21
	v_pk_fma_f32 v[6:7], v[92:93], v[28:29], v[6:7] op_sel_hi:[0,1,1]
	global_load_dword v78, v[142:143], off
	global_load_dword v80, v[144:145], off
	global_load_dword v82, v[146:147], off
	global_load_dword v84, v[148:149], off
	global_load_dword v86, v[150:151], off
	global_load_dword v88, v[152:153], off
	global_load_dword v90, v[154:155], off
	global_load_dword v92, v[156:157], off
	v_lshl_add_u64 v[142:143], v[142:143], 0, s[10:11]
	v_lshl_add_u64 v[144:145], v[144:145], 0, s[10:11]
	v_lshl_add_u64 v[146:147], v[146:147], 0, s[10:11]
	v_lshl_add_u64 v[148:149], v[148:149], 0, s[10:11]
	v_lshl_add_u64 v[150:151], v[150:151], 0, s[10:11]
	v_lshl_add_u64 v[152:153], v[152:153], 0, s[10:11]
	v_lshl_add_u64 v[154:155], v[154:155], 0, s[10:11]
	v_lshl_add_u64 v[156:157], v[156:157], 0, s[10:11]
	ds_read_b128 v[14:17], v12
	ds_read_b128 v[18:21], v12 offset:16
	ds_read_b128 v[22:25], v12 offset:4096
	ds_read_b128 v[26:29], v12 offset:4112
	ds_read_b128 v[30:33], v12 offset:8192
	ds_read_b128 v[34:37], v12 offset:8208
	v_add_u32_e32 v12, 32, v12
	s_waitcnt lgkmcnt(3)
	v_mov_b32_e32 v55, v22
	s_waitcnt lgkmcnt(1)
	v_mov_b32_e32 v54, v30
	v_mov_b32_e32 v22, v31
	v_mov_b32_e32 v30, v32
	v_mov_b32_e32 v31, v24
	v_mov_b32_e32 v24, v33
	s_waitcnt lgkmcnt(0)
	v_mov_b32_e32 v32, v34
	v_mov_b32_e32 v33, v26
	v_mov_b32_e32 v26, v35
	v_mov_b32_e32 v34, v36
	v_mov_b32_e32 v35, v28
	v_mov_b32_e32 v28, v37
	s_waitcnt vmcnt(24)
	v_fmac_f32_e32 v11, v94, v14
	v_pk_fma_f32 v[6:7], v[94:95], v[54:55], v[6:7] op_sel_hi:[0,1,1]
	v_fmac_f32_e32 v11, v96, v15
	v_pk_fma_f32 v[6:7], v[96:97], v[22:23], v[6:7] op_sel_hi:[0,1,1]
	v_fmac_f32_e32 v11, v102, v16
	v_pk_fma_f32 v[6:7], v[102:103], v[30:31], v[6:7] op_sel_hi:[0,1,1]
	v_fmac_f32_e32 v11, v104, v17
	v_pk_fma_f32 v[6:7], v[104:105], v[24:25], v[6:7] op_sel_hi:[0,1,1]
	v_fmac_f32_e32 v11, v106, v18
	v_pk_fma_f32 v[6:7], v[106:107], v[32:33], v[6:7] op_sel_hi:[0,1,1]
	v_fmac_f32_e32 v11, v110, v19
	v_pk_fma_f32 v[6:7], v[110:111], v[26:27], v[6:7] op_sel_hi:[0,1,1]
	v_fmac_f32_e32 v11, v114, v20
	v_pk_fma_f32 v[6:7], v[114:115], v[34:35], v[6:7] op_sel_hi:[0,1,1]
	v_fmac_f32_e32 v11, v116, v21
	v_pk_fma_f32 v[6:7], v[116:117], v[28:29], v[6:7] op_sel_hi:[0,1,1]
	global_load_dword v94, v[142:143], off
	global_load_dword v96, v[144:145], off
	global_load_dword v102, v[146:147], off
	global_load_dword v104, v[148:149], off
	global_load_dword v106, v[150:151], off
	global_load_dword v110, v[152:153], off
	global_load_dword v114, v[154:155], off
	global_load_dword v116, v[156:157], off
	v_lshl_add_u64 v[142:143], v[142:143], 0, s[10:11]
	v_lshl_add_u64 v[144:145], v[144:145], 0, s[10:11]
	v_lshl_add_u64 v[146:147], v[146:147], 0, s[10:11]
	v_lshl_add_u64 v[148:149], v[148:149], 0, s[10:11]
	v_lshl_add_u64 v[150:151], v[150:151], 0, s[10:11]
	v_lshl_add_u64 v[152:153], v[152:153], 0, s[10:11]
	v_lshl_add_u64 v[154:155], v[154:155], 0, s[10:11]
	v_lshl_add_u64 v[156:157], v[156:157], 0, s[10:11]
	ds_read_b128 v[14:17], v12
	ds_read_b128 v[18:21], v12 offset:16
	ds_read_b128 v[22:25], v12 offset:4096
	ds_read_b128 v[26:29], v12 offset:4112
	ds_read_b128 v[30:33], v12 offset:8192
	ds_read_b128 v[34:37], v12 offset:8208
	v_add_u32_e32 v12, 32, v12
	s_waitcnt lgkmcnt(3)
	v_mov_b32_e32 v55, v22
	s_waitcnt lgkmcnt(1)
	v_mov_b32_e32 v54, v30
	v_mov_b32_e32 v22, v31
	v_mov_b32_e32 v30, v32
	v_mov_b32_e32 v31, v24
	v_mov_b32_e32 v24, v33
	s_waitcnt lgkmcnt(0)
	v_mov_b32_e32 v32, v34
	v_mov_b32_e32 v33, v26
	v_mov_b32_e32 v26, v35
	v_mov_b32_e32 v34, v36
	v_mov_b32_e32 v35, v28
	v_mov_b32_e32 v28, v37
	s_waitcnt vmcnt(24)
	v_fmac_f32_e32 v11, v38, v14
	v_pk_fma_f32 v[6:7], v[38:39], v[54:55], v[6:7] op_sel_hi:[0,1,1]
	v_fmac_f32_e32 v11, v40, v15
	v_pk_fma_f32 v[6:7], v[40:41], v[22:23], v[6:7] op_sel_hi:[0,1,1]
	v_fmac_f32_e32 v11, v42, v16
	v_pk_fma_f32 v[6:7], v[42:43], v[30:31], v[6:7] op_sel_hi:[0,1,1]
	v_fmac_f32_e32 v11, v44, v17
	v_pk_fma_f32 v[6:7], v[44:45], v[24:25], v[6:7] op_sel_hi:[0,1,1]
	v_fmac_f32_e32 v11, v46, v18
	v_pk_fma_f32 v[6:7], v[46:47], v[32:33], v[6:7] op_sel_hi:[0,1,1]
	v_fmac_f32_e32 v11, v48, v19
	v_pk_fma_f32 v[6:7], v[48:49], v[26:27], v[6:7] op_sel_hi:[0,1,1]
	v_fmac_f32_e32 v11, v50, v20
	v_pk_fma_f32 v[6:7], v[50:51], v[34:35], v[6:7] op_sel_hi:[0,1,1]
	v_fmac_f32_e32 v11, v52, v21
	v_pk_fma_f32 v[6:7], v[52:53], v[28:29], v[6:7] op_sel_hi:[0,1,1]
	global_load_dword v38, v[142:143], off
	global_load_dword v40, v[144:145], off
	global_load_dword v42, v[146:147], off
	global_load_dword v44, v[148:149], off
	global_load_dword v46, v[150:151], off
	global_load_dword v48, v[152:153], off
	global_load_dword v50, v[154:155], off
	global_load_dword v52, v[156:157], off
	v_lshl_add_u64 v[142:143], v[142:143], 0, s[10:11]
	v_lshl_add_u64 v[144:145], v[144:145], 0, s[10:11]
	v_lshl_add_u64 v[146:147], v[146:147], 0, s[10:11]
	v_lshl_add_u64 v[148:149], v[148:149], 0, s[10:11]
	v_lshl_add_u64 v[150:151], v[150:151], 0, s[10:11]
	v_lshl_add_u64 v[152:153], v[152:153], 0, s[10:11]
	v_lshl_add_u64 v[154:155], v[154:155], 0, s[10:11]
	v_lshl_add_u64 v[156:157], v[156:157], 0, s[10:11]
	ds_read_b128 v[14:17], v12
	ds_read_b128 v[18:21], v12 offset:16
	ds_read_b128 v[22:25], v12 offset:4096
	ds_read_b128 v[26:29], v12 offset:4112
	ds_read_b128 v[30:33], v12 offset:8192
	ds_read_b128 v[34:37], v12 offset:8208
	v_add_u32_e32 v12, 32, v12
	s_waitcnt lgkmcnt(3)
	v_mov_b32_e32 v55, v22
	s_waitcnt lgkmcnt(1)
	v_mov_b32_e32 v54, v30
	v_mov_b32_e32 v22, v31
	v_mov_b32_e32 v30, v32
	v_mov_b32_e32 v31, v24
	v_mov_b32_e32 v24, v33
	s_waitcnt lgkmcnt(0)
	v_mov_b32_e32 v32, v34
	v_mov_b32_e32 v33, v26
	v_mov_b32_e32 v26, v35
	v_mov_b32_e32 v34, v36
	v_mov_b32_e32 v35, v28
	v_mov_b32_e32 v28, v37
	s_waitcnt vmcnt(24)
	v_fmac_f32_e32 v11, v62, v14
	v_pk_fma_f32 v[6:7], v[62:63], v[54:55], v[6:7] op_sel_hi:[0,1,1]
	v_fmac_f32_e32 v11, v64, v15
	v_pk_fma_f32 v[6:7], v[64:65], v[22:23], v[6:7] op_sel_hi:[0,1,1]
	v_fmac_f32_e32 v11, v66, v16
	v_pk_fma_f32 v[6:7], v[66:67], v[30:31], v[6:7] op_sel_hi:[0,1,1]
	v_fmac_f32_e32 v11, v68, v17
	v_pk_fma_f32 v[6:7], v[68:69], v[24:25], v[6:7] op_sel_hi:[0,1,1]
	v_fmac_f32_e32 v11, v70, v18
	v_pk_fma_f32 v[6:7], v[70:71], v[32:33], v[6:7] op_sel_hi:[0,1,1]
	v_fmac_f32_e32 v11, v72, v19
	v_pk_fma_f32 v[6:7], v[72:73], v[26:27], v[6:7] op_sel_hi:[0,1,1]
	v_fmac_f32_e32 v11, v74, v20
	v_pk_fma_f32 v[6:7], v[74:75], v[34:35], v[6:7] op_sel_hi:[0,1,1]
	v_fmac_f32_e32 v11, v76, v21
	v_pk_fma_f32 v[6:7], v[76:77], v[28:29], v[6:7] op_sel_hi:[0,1,1]
	global_load_dword v62, v[142:143], off
	global_load_dword v64, v[144:145], off
	global_load_dword v66, v[146:147], off
	global_load_dword v68, v[148:149], off
	global_load_dword v70, v[150:151], off
	global_load_dword v72, v[152:153], off
	global_load_dword v74, v[154:155], off
	global_load_dword v76, v[156:157], off
	v_lshl_add_u64 v[142:143], v[142:143], 0, s[10:11]
	v_lshl_add_u64 v[144:145], v[144:145], 0, s[10:11]
	v_lshl_add_u64 v[146:147], v[146:147], 0, s[10:11]
	v_lshl_add_u64 v[148:149], v[148:149], 0, s[10:11]
	v_lshl_add_u64 v[150:151], v[150:151], 0, s[10:11]
	v_lshl_add_u64 v[152:153], v[152:153], 0, s[10:11]
	v_lshl_add_u64 v[154:155], v[154:155], 0, s[10:11]
	v_lshl_add_u64 v[156:157], v[156:157], 0, s[10:11]
	ds_read_b128 v[14:17], v12
	ds_read_b128 v[18:21], v12 offset:16
	ds_read_b128 v[22:25], v12 offset:4096
	ds_read_b128 v[26:29], v12 offset:4112
	ds_read_b128 v[30:33], v12 offset:8192
	ds_read_b128 v[34:37], v12 offset:8208
	v_add_u32_e32 v12, 32, v12
	s_waitcnt lgkmcnt(3)
	v_mov_b32_e32 v55, v22
	s_waitcnt lgkmcnt(1)
	v_mov_b32_e32 v54, v30
	v_mov_b32_e32 v22, v31
	v_mov_b32_e32 v30, v32
	v_mov_b32_e32 v31, v24
	v_mov_b32_e32 v24, v33
	s_waitcnt lgkmcnt(0)
	v_mov_b32_e32 v32, v34
	v_mov_b32_e32 v33, v26
	v_mov_b32_e32 v26, v35
	v_mov_b32_e32 v34, v36
	v_mov_b32_e32 v35, v28
	v_mov_b32_e32 v28, v37
	s_waitcnt vmcnt(24)
	v_fmac_f32_e32 v11, v78, v14
	v_pk_fma_f32 v[6:7], v[78:79], v[54:55], v[6:7] op_sel_hi:[0,1,1]
	v_fmac_f32_e32 v11, v80, v15
	v_pk_fma_f32 v[6:7], v[80:81], v[22:23], v[6:7] op_sel_hi:[0,1,1]
	v_fmac_f32_e32 v11, v82, v16
	v_pk_fma_f32 v[6:7], v[82:83], v[30:31], v[6:7] op_sel_hi:[0,1,1]
	v_fmac_f32_e32 v11, v84, v17
	v_pk_fma_f32 v[6:7], v[84:85], v[24:25], v[6:7] op_sel_hi:[0,1,1]
	v_fmac_f32_e32 v11, v86, v18
	v_pk_fma_f32 v[6:7], v[86:87], v[32:33], v[6:7] op_sel_hi:[0,1,1]
	v_fmac_f32_e32 v11, v88, v19
	v_pk_fma_f32 v[6:7], v[88:89], v[26:27], v[6:7] op_sel_hi:[0,1,1]
	v_fmac_f32_e32 v11, v90, v20
	v_pk_fma_f32 v[6:7], v[90:91], v[34:35], v[6:7] op_sel_hi:[0,1,1]
	v_fmac_f32_e32 v11, v92, v21
	v_pk_fma_f32 v[6:7], v[92:93], v[28:29], v[6:7] op_sel_hi:[0,1,1]
	global_load_dword v78, v[142:143], off
	global_load_dword v80, v[144:145], off
	global_load_dword v82, v[146:147], off
	global_load_dword v84, v[148:149], off
	global_load_dword v86, v[150:151], off
	global_load_dword v88, v[152:153], off
	global_load_dword v90, v[154:155], off
	global_load_dword v92, v[156:157], off
	v_lshl_add_u64 v[142:143], v[142:143], 0, s[10:11]
	v_lshl_add_u64 v[144:145], v[144:145], 0, s[10:11]
	v_lshl_add_u64 v[146:147], v[146:147], 0, s[10:11]
	v_lshl_add_u64 v[148:149], v[148:149], 0, s[10:11]
	v_lshl_add_u64 v[150:151], v[150:151], 0, s[10:11]
	v_lshl_add_u64 v[152:153], v[152:153], 0, s[10:11]
	v_lshl_add_u64 v[154:155], v[154:155], 0, s[10:11]
	v_lshl_add_u64 v[156:157], v[156:157], 0, s[10:11]
	ds_read_b128 v[14:17], v12
	ds_read_b128 v[18:21], v12 offset:16
	ds_read_b128 v[22:25], v12 offset:4096
	ds_read_b128 v[26:29], v12 offset:4112
	ds_read_b128 v[30:33], v12 offset:8192
	ds_read_b128 v[34:37], v12 offset:8208
	v_add_u32_e32 v12, 32, v12
	s_waitcnt lgkmcnt(3)
	v_mov_b32_e32 v55, v22
	s_waitcnt lgkmcnt(1)
	v_mov_b32_e32 v54, v30
	v_mov_b32_e32 v22, v31
	v_mov_b32_e32 v30, v32
	v_mov_b32_e32 v31, v24
	v_mov_b32_e32 v24, v33
	s_waitcnt lgkmcnt(0)
	v_mov_b32_e32 v32, v34
	v_mov_b32_e32 v33, v26
	v_mov_b32_e32 v26, v35
	v_mov_b32_e32 v34, v36
	v_mov_b32_e32 v35, v28
	v_mov_b32_e32 v28, v37
	s_waitcnt vmcnt(24)
	v_fmac_f32_e32 v11, v94, v14
	v_pk_fma_f32 v[6:7], v[94:95], v[54:55], v[6:7] op_sel_hi:[0,1,1]
	v_fmac_f32_e32 v11, v96, v15
	v_pk_fma_f32 v[6:7], v[96:97], v[22:23], v[6:7] op_sel_hi:[0,1,1]
	v_fmac_f32_e32 v11, v102, v16
	v_pk_fma_f32 v[6:7], v[102:103], v[30:31], v[6:7] op_sel_hi:[0,1,1]
	v_fmac_f32_e32 v11, v104, v17
	v_pk_fma_f32 v[6:7], v[104:105], v[24:25], v[6:7] op_sel_hi:[0,1,1]
	v_fmac_f32_e32 v11, v106, v18
	v_pk_fma_f32 v[6:7], v[106:107], v[32:33], v[6:7] op_sel_hi:[0,1,1]
	v_fmac_f32_e32 v11, v110, v19
	v_pk_fma_f32 v[6:7], v[110:111], v[26:27], v[6:7] op_sel_hi:[0,1,1]
	v_fmac_f32_e32 v11, v114, v20
	v_pk_fma_f32 v[6:7], v[114:115], v[34:35], v[6:7] op_sel_hi:[0,1,1]
	v_fmac_f32_e32 v11, v116, v21
	v_pk_fma_f32 v[6:7], v[116:117], v[28:29], v[6:7] op_sel_hi:[0,1,1]
	global_load_dword v94, v[142:143], off
	global_load_dword v96, v[144:145], off
	global_load_dword v102, v[146:147], off
	global_load_dword v104, v[148:149], off
	global_load_dword v106, v[150:151], off
	global_load_dword v110, v[152:153], off
	global_load_dword v114, v[154:155], off
	global_load_dword v116, v[156:157], off
	v_lshl_add_u64 v[142:143], v[142:143], 0, s[10:11]
	v_lshl_add_u64 v[144:145], v[144:145], 0, s[10:11]
	v_lshl_add_u64 v[146:147], v[146:147], 0, s[10:11]
	v_lshl_add_u64 v[148:149], v[148:149], 0, s[10:11]
	v_lshl_add_u64 v[150:151], v[150:151], 0, s[10:11]
	v_lshl_add_u64 v[152:153], v[152:153], 0, s[10:11]
	v_lshl_add_u64 v[154:155], v[154:155], 0, s[10:11]
	v_lshl_add_u64 v[156:157], v[156:157], 0, s[10:11]
	ds_read_b128 v[14:17], v12
	ds_read_b128 v[18:21], v12 offset:16
	ds_read_b128 v[22:25], v12 offset:4096
	ds_read_b128 v[26:29], v12 offset:4112
	ds_read_b128 v[30:33], v12 offset:8192
	ds_read_b128 v[34:37], v12 offset:8208
	v_add_u32_e32 v12, 32, v12
	s_waitcnt lgkmcnt(3)
	v_mov_b32_e32 v55, v22
	s_waitcnt lgkmcnt(1)
	v_mov_b32_e32 v54, v30
	v_mov_b32_e32 v22, v31
	v_mov_b32_e32 v30, v32
	v_mov_b32_e32 v31, v24
	v_mov_b32_e32 v24, v33
	s_waitcnt lgkmcnt(0)
	v_mov_b32_e32 v32, v34
	v_mov_b32_e32 v33, v26
	v_mov_b32_e32 v26, v35
	v_mov_b32_e32 v34, v36
	v_mov_b32_e32 v35, v28
	v_mov_b32_e32 v28, v37
	s_waitcnt vmcnt(24)
	v_fmac_f32_e32 v11, v38, v14
	v_pk_fma_f32 v[6:7], v[38:39], v[54:55], v[6:7] op_sel_hi:[0,1,1]
	v_fmac_f32_e32 v11, v40, v15
	v_pk_fma_f32 v[6:7], v[40:41], v[22:23], v[6:7] op_sel_hi:[0,1,1]
	v_fmac_f32_e32 v11, v42, v16
	v_pk_fma_f32 v[6:7], v[42:43], v[30:31], v[6:7] op_sel_hi:[0,1,1]
	v_fmac_f32_e32 v11, v44, v17
	v_pk_fma_f32 v[6:7], v[44:45], v[24:25], v[6:7] op_sel_hi:[0,1,1]
	v_fmac_f32_e32 v11, v46, v18
	v_pk_fma_f32 v[6:7], v[46:47], v[32:33], v[6:7] op_sel_hi:[0,1,1]
	v_fmac_f32_e32 v11, v48, v19
	v_pk_fma_f32 v[6:7], v[48:49], v[26:27], v[6:7] op_sel_hi:[0,1,1]
	v_fmac_f32_e32 v11, v50, v20
	v_pk_fma_f32 v[6:7], v[50:51], v[34:35], v[6:7] op_sel_hi:[0,1,1]
	v_fmac_f32_e32 v11, v52, v21
	v_pk_fma_f32 v[6:7], v[52:53], v[28:29], v[6:7] op_sel_hi:[0,1,1]
	global_load_dword v38, v[142:143], off
	global_load_dword v40, v[144:145], off
	global_load_dword v42, v[146:147], off
	global_load_dword v44, v[148:149], off
	global_load_dword v46, v[150:151], off
	global_load_dword v48, v[152:153], off
	global_load_dword v50, v[154:155], off
	global_load_dword v52, v[156:157], off
	v_lshl_add_u64 v[142:143], v[142:143], 0, s[10:11]
	v_lshl_add_u64 v[144:145], v[144:145], 0, s[10:11]
	v_lshl_add_u64 v[146:147], v[146:147], 0, s[10:11]
	v_lshl_add_u64 v[148:149], v[148:149], 0, s[10:11]
	v_lshl_add_u64 v[150:151], v[150:151], 0, s[10:11]
	v_lshl_add_u64 v[152:153], v[152:153], 0, s[10:11]
	v_lshl_add_u64 v[154:155], v[154:155], 0, s[10:11]
	v_lshl_add_u64 v[156:157], v[156:157], 0, s[10:11]
	ds_read_b128 v[14:17], v12
	ds_read_b128 v[18:21], v12 offset:16
	ds_read_b128 v[22:25], v12 offset:4096
	ds_read_b128 v[26:29], v12 offset:4112
	ds_read_b128 v[30:33], v12 offset:8192
	ds_read_b128 v[34:37], v12 offset:8208
	v_add_u32_e32 v12, 32, v12
	s_waitcnt lgkmcnt(3)
	v_mov_b32_e32 v55, v22
	s_waitcnt lgkmcnt(1)
	v_mov_b32_e32 v54, v30
	v_mov_b32_e32 v22, v31
	v_mov_b32_e32 v30, v32
	v_mov_b32_e32 v31, v24
	v_mov_b32_e32 v24, v33
	s_waitcnt lgkmcnt(0)
	v_mov_b32_e32 v32, v34
	v_mov_b32_e32 v33, v26
	v_mov_b32_e32 v26, v35
	v_mov_b32_e32 v34, v36
	v_mov_b32_e32 v35, v28
	v_mov_b32_e32 v28, v37
	s_waitcnt vmcnt(24)
	v_fmac_f32_e32 v11, v62, v14
	v_pk_fma_f32 v[6:7], v[62:63], v[54:55], v[6:7] op_sel_hi:[0,1,1]
	v_fmac_f32_e32 v11, v64, v15
	v_pk_fma_f32 v[6:7], v[64:65], v[22:23], v[6:7] op_sel_hi:[0,1,1]
	v_fmac_f32_e32 v11, v66, v16
	v_pk_fma_f32 v[6:7], v[66:67], v[30:31], v[6:7] op_sel_hi:[0,1,1]
	v_fmac_f32_e32 v11, v68, v17
	v_pk_fma_f32 v[6:7], v[68:69], v[24:25], v[6:7] op_sel_hi:[0,1,1]
	v_fmac_f32_e32 v11, v70, v18
	v_pk_fma_f32 v[6:7], v[70:71], v[32:33], v[6:7] op_sel_hi:[0,1,1]
	v_fmac_f32_e32 v11, v72, v19
	v_pk_fma_f32 v[6:7], v[72:73], v[26:27], v[6:7] op_sel_hi:[0,1,1]
	v_fmac_f32_e32 v11, v74, v20
	v_pk_fma_f32 v[6:7], v[74:75], v[34:35], v[6:7] op_sel_hi:[0,1,1]
	v_fmac_f32_e32 v11, v76, v21
	v_pk_fma_f32 v[6:7], v[76:77], v[28:29], v[6:7] op_sel_hi:[0,1,1]
	global_load_dword v62, v[142:143], off
	global_load_dword v64, v[144:145], off
	global_load_dword v66, v[146:147], off
	global_load_dword v68, v[148:149], off
	global_load_dword v70, v[150:151], off
	global_load_dword v72, v[152:153], off
	global_load_dword v74, v[154:155], off
	global_load_dword v76, v[156:157], off
	v_lshl_add_u64 v[142:143], v[142:143], 0, s[10:11]
	v_lshl_add_u64 v[144:145], v[144:145], 0, s[10:11]
	v_lshl_add_u64 v[146:147], v[146:147], 0, s[10:11]
	v_lshl_add_u64 v[148:149], v[148:149], 0, s[10:11]
	v_lshl_add_u64 v[150:151], v[150:151], 0, s[10:11]
	v_lshl_add_u64 v[152:153], v[152:153], 0, s[10:11]
	v_lshl_add_u64 v[154:155], v[154:155], 0, s[10:11]
	v_lshl_add_u64 v[156:157], v[156:157], 0, s[10:11]
	ds_read_b128 v[14:17], v12
	ds_read_b128 v[18:21], v12 offset:16
	ds_read_b128 v[22:25], v12 offset:4096
	ds_read_b128 v[26:29], v12 offset:4112
	ds_read_b128 v[30:33], v12 offset:8192
	ds_read_b128 v[34:37], v12 offset:8208
	v_add_u32_e32 v12, 32, v12
	s_waitcnt lgkmcnt(3)
	v_mov_b32_e32 v55, v22
	s_waitcnt lgkmcnt(1)
	v_mov_b32_e32 v54, v30
	v_mov_b32_e32 v22, v31
	v_mov_b32_e32 v30, v32
	v_mov_b32_e32 v31, v24
	v_mov_b32_e32 v24, v33
	s_waitcnt lgkmcnt(0)
	v_mov_b32_e32 v32, v34
	v_mov_b32_e32 v33, v26
	v_mov_b32_e32 v26, v35
	v_mov_b32_e32 v34, v36
	v_mov_b32_e32 v35, v28
	v_mov_b32_e32 v28, v37
	s_waitcnt vmcnt(24)
	v_fmac_f32_e32 v11, v78, v14
	v_pk_fma_f32 v[6:7], v[78:79], v[54:55], v[6:7] op_sel_hi:[0,1,1]
	v_fmac_f32_e32 v11, v80, v15
	v_pk_fma_f32 v[6:7], v[80:81], v[22:23], v[6:7] op_sel_hi:[0,1,1]
	v_fmac_f32_e32 v11, v82, v16
	v_pk_fma_f32 v[6:7], v[82:83], v[30:31], v[6:7] op_sel_hi:[0,1,1]
	v_fmac_f32_e32 v11, v84, v17
	v_pk_fma_f32 v[6:7], v[84:85], v[24:25], v[6:7] op_sel_hi:[0,1,1]
	v_fmac_f32_e32 v11, v86, v18
	v_pk_fma_f32 v[6:7], v[86:87], v[32:33], v[6:7] op_sel_hi:[0,1,1]
	v_fmac_f32_e32 v11, v88, v19
	v_pk_fma_f32 v[6:7], v[88:89], v[26:27], v[6:7] op_sel_hi:[0,1,1]
	v_fmac_f32_e32 v11, v90, v20
	v_pk_fma_f32 v[6:7], v[90:91], v[34:35], v[6:7] op_sel_hi:[0,1,1]
	v_fmac_f32_e32 v11, v92, v21
	v_pk_fma_f32 v[6:7], v[92:93], v[28:29], v[6:7] op_sel_hi:[0,1,1]
	global_load_dword v78, v[142:143], off
	global_load_dword v80, v[144:145], off
	global_load_dword v82, v[146:147], off
	global_load_dword v84, v[148:149], off
	global_load_dword v86, v[150:151], off
	global_load_dword v88, v[152:153], off
	global_load_dword v90, v[154:155], off
	global_load_dword v92, v[156:157], off
	v_lshl_add_u64 v[142:143], v[142:143], 0, s[10:11]
	v_lshl_add_u64 v[144:145], v[144:145], 0, s[10:11]
	v_lshl_add_u64 v[146:147], v[146:147], 0, s[10:11]
	v_lshl_add_u64 v[148:149], v[148:149], 0, s[10:11]
	v_lshl_add_u64 v[150:151], v[150:151], 0, s[10:11]
	v_lshl_add_u64 v[152:153], v[152:153], 0, s[10:11]
	v_lshl_add_u64 v[154:155], v[154:155], 0, s[10:11]
	v_lshl_add_u64 v[156:157], v[156:157], 0, s[10:11]
	ds_read_b128 v[14:17], v12
	ds_read_b128 v[18:21], v12 offset:16
	ds_read_b128 v[22:25], v12 offset:4096
	ds_read_b128 v[26:29], v12 offset:4112
	ds_read_b128 v[30:33], v12 offset:8192
	ds_read_b128 v[34:37], v12 offset:8208
	v_add_u32_e32 v12, 32, v12
	s_waitcnt lgkmcnt(3)
	v_mov_b32_e32 v55, v22
	s_waitcnt lgkmcnt(1)
	v_mov_b32_e32 v54, v30
	v_mov_b32_e32 v22, v31
	v_mov_b32_e32 v30, v32
	v_mov_b32_e32 v31, v24
	v_mov_b32_e32 v24, v33
	s_waitcnt lgkmcnt(0)
	v_mov_b32_e32 v32, v34
	v_mov_b32_e32 v33, v26
	v_mov_b32_e32 v26, v35
	v_mov_b32_e32 v34, v36
	v_mov_b32_e32 v35, v28
	v_mov_b32_e32 v28, v37
	s_waitcnt vmcnt(24)
	v_fmac_f32_e32 v11, v94, v14
	v_pk_fma_f32 v[6:7], v[94:95], v[54:55], v[6:7] op_sel_hi:[0,1,1]
	v_fmac_f32_e32 v11, v96, v15
	v_pk_fma_f32 v[6:7], v[96:97], v[22:23], v[6:7] op_sel_hi:[0,1,1]
	v_fmac_f32_e32 v11, v102, v16
	v_pk_fma_f32 v[6:7], v[102:103], v[30:31], v[6:7] op_sel_hi:[0,1,1]
	v_fmac_f32_e32 v11, v104, v17
	v_pk_fma_f32 v[6:7], v[104:105], v[24:25], v[6:7] op_sel_hi:[0,1,1]
	v_fmac_f32_e32 v11, v106, v18
	v_pk_fma_f32 v[6:7], v[106:107], v[32:33], v[6:7] op_sel_hi:[0,1,1]
	v_fmac_f32_e32 v11, v110, v19
	v_pk_fma_f32 v[6:7], v[110:111], v[26:27], v[6:7] op_sel_hi:[0,1,1]
	v_fmac_f32_e32 v11, v114, v20
	v_pk_fma_f32 v[6:7], v[114:115], v[34:35], v[6:7] op_sel_hi:[0,1,1]
	v_fmac_f32_e32 v11, v116, v21
	v_pk_fma_f32 v[6:7], v[116:117], v[28:29], v[6:7] op_sel_hi:[0,1,1]
	global_load_dword v94, v[142:143], off
	global_load_dword v96, v[144:145], off
	global_load_dword v102, v[146:147], off
	global_load_dword v104, v[148:149], off
	global_load_dword v106, v[150:151], off
	global_load_dword v110, v[152:153], off
	global_load_dword v114, v[154:155], off
	global_load_dword v116, v[156:157], off
	v_lshl_add_u64 v[142:143], v[142:143], 0, s[10:11]
	v_lshl_add_u64 v[144:145], v[144:145], 0, s[10:11]
	v_lshl_add_u64 v[146:147], v[146:147], 0, s[10:11]
	v_lshl_add_u64 v[148:149], v[148:149], 0, s[10:11]
	v_lshl_add_u64 v[150:151], v[150:151], 0, s[10:11]
	v_lshl_add_u64 v[152:153], v[152:153], 0, s[10:11]
	v_lshl_add_u64 v[154:155], v[154:155], 0, s[10:11]
	v_lshl_add_u64 v[156:157], v[156:157], 0, s[10:11]
	ds_read_b128 v[14:17], v12
	ds_read_b128 v[18:21], v12 offset:16
	ds_read_b128 v[22:25], v12 offset:4096
	ds_read_b128 v[26:29], v12 offset:4112
	ds_read_b128 v[30:33], v12 offset:8192
	ds_read_b128 v[34:37], v12 offset:8208
	v_add_u32_e32 v12, 32, v12
	s_waitcnt lgkmcnt(3)
	v_mov_b32_e32 v55, v22
	s_waitcnt lgkmcnt(1)
	v_mov_b32_e32 v54, v30
	v_mov_b32_e32 v22, v31
	v_mov_b32_e32 v30, v32
	v_mov_b32_e32 v31, v24
	v_mov_b32_e32 v24, v33
	s_waitcnt lgkmcnt(0)
	v_mov_b32_e32 v32, v34
	v_mov_b32_e32 v33, v26
	v_mov_b32_e32 v26, v35
	v_mov_b32_e32 v34, v36
	v_mov_b32_e32 v35, v28
	v_mov_b32_e32 v28, v37
	s_waitcnt vmcnt(24)
	v_fmac_f32_e32 v11, v38, v14
	v_pk_fma_f32 v[6:7], v[38:39], v[54:55], v[6:7] op_sel_hi:[0,1,1]
	v_fmac_f32_e32 v11, v40, v15
	v_pk_fma_f32 v[6:7], v[40:41], v[22:23], v[6:7] op_sel_hi:[0,1,1]
	v_fmac_f32_e32 v11, v42, v16
	v_pk_fma_f32 v[6:7], v[42:43], v[30:31], v[6:7] op_sel_hi:[0,1,1]
	v_fmac_f32_e32 v11, v44, v17
	v_pk_fma_f32 v[6:7], v[44:45], v[24:25], v[6:7] op_sel_hi:[0,1,1]
	v_fmac_f32_e32 v11, v46, v18
	v_pk_fma_f32 v[6:7], v[46:47], v[32:33], v[6:7] op_sel_hi:[0,1,1]
	v_fmac_f32_e32 v11, v48, v19
	v_pk_fma_f32 v[6:7], v[48:49], v[26:27], v[6:7] op_sel_hi:[0,1,1]
	v_fmac_f32_e32 v11, v50, v20
	v_pk_fma_f32 v[6:7], v[50:51], v[34:35], v[6:7] op_sel_hi:[0,1,1]
	v_fmac_f32_e32 v11, v52, v21
	v_pk_fma_f32 v[6:7], v[52:53], v[28:29], v[6:7] op_sel_hi:[0,1,1]
	ds_read_b128 v[14:17], v12
	ds_read_b128 v[18:21], v12 offset:16
	ds_read_b128 v[22:25], v12 offset:4096
	ds_read_b128 v[26:29], v12 offset:4112
	ds_read_b128 v[30:33], v12 offset:8192
	ds_read_b128 v[34:37], v12 offset:8208
	v_add_u32_e32 v12, 32, v12
	s_waitcnt lgkmcnt(3)
	v_mov_b32_e32 v55, v22
	s_waitcnt lgkmcnt(1)
	v_mov_b32_e32 v54, v30
	v_mov_b32_e32 v22, v31
	v_mov_b32_e32 v30, v32
	v_mov_b32_e32 v31, v24
	v_mov_b32_e32 v24, v33
	s_waitcnt lgkmcnt(0)
	v_mov_b32_e32 v32, v34
	v_mov_b32_e32 v33, v26
	v_mov_b32_e32 v26, v35
	v_mov_b32_e32 v34, v36
	v_mov_b32_e32 v35, v28
	v_mov_b32_e32 v28, v37
	s_waitcnt vmcnt(16)
	v_fmac_f32_e32 v11, v62, v14
	v_pk_fma_f32 v[6:7], v[62:63], v[54:55], v[6:7] op_sel_hi:[0,1,1]
	v_fmac_f32_e32 v11, v64, v15
	v_pk_fma_f32 v[6:7], v[64:65], v[22:23], v[6:7] op_sel_hi:[0,1,1]
	v_fmac_f32_e32 v11, v66, v16
	v_pk_fma_f32 v[6:7], v[66:67], v[30:31], v[6:7] op_sel_hi:[0,1,1]
	v_fmac_f32_e32 v11, v68, v17
	v_pk_fma_f32 v[6:7], v[68:69], v[24:25], v[6:7] op_sel_hi:[0,1,1]
	v_fmac_f32_e32 v11, v70, v18
	v_pk_fma_f32 v[6:7], v[70:71], v[32:33], v[6:7] op_sel_hi:[0,1,1]
	v_fmac_f32_e32 v11, v72, v19
	v_pk_fma_f32 v[6:7], v[72:73], v[26:27], v[6:7] op_sel_hi:[0,1,1]
	v_fmac_f32_e32 v11, v74, v20
	v_pk_fma_f32 v[6:7], v[74:75], v[34:35], v[6:7] op_sel_hi:[0,1,1]
	v_fmac_f32_e32 v11, v76, v21
	v_pk_fma_f32 v[6:7], v[76:77], v[28:29], v[6:7] op_sel_hi:[0,1,1]
	ds_read_b128 v[14:17], v12
	ds_read_b128 v[18:21], v12 offset:16
	ds_read_b128 v[22:25], v12 offset:4096
	ds_read_b128 v[26:29], v12 offset:4112
	ds_read_b128 v[30:33], v12 offset:8192
	ds_read_b128 v[34:37], v12 offset:8208
	v_add_u32_e32 v12, 32, v12
	s_waitcnt lgkmcnt(3)
	v_mov_b32_e32 v55, v22
	s_waitcnt lgkmcnt(1)
	v_mov_b32_e32 v54, v30
	v_mov_b32_e32 v22, v31
	v_mov_b32_e32 v30, v32
	v_mov_b32_e32 v31, v24
	v_mov_b32_e32 v24, v33
	s_waitcnt lgkmcnt(0)
	v_mov_b32_e32 v32, v34
	v_mov_b32_e32 v33, v26
	v_mov_b32_e32 v26, v35
	v_mov_b32_e32 v34, v36
	v_mov_b32_e32 v35, v28
	v_mov_b32_e32 v28, v37
	s_waitcnt vmcnt(8)
	v_fmac_f32_e32 v11, v78, v14
	v_pk_fma_f32 v[6:7], v[78:79], v[54:55], v[6:7] op_sel_hi:[0,1,1]
	v_fmac_f32_e32 v11, v80, v15
	v_pk_fma_f32 v[6:7], v[80:81], v[22:23], v[6:7] op_sel_hi:[0,1,1]
	v_fmac_f32_e32 v11, v82, v16
	v_pk_fma_f32 v[6:7], v[82:83], v[30:31], v[6:7] op_sel_hi:[0,1,1]
	v_fmac_f32_e32 v11, v84, v17
	v_pk_fma_f32 v[6:7], v[84:85], v[24:25], v[6:7] op_sel_hi:[0,1,1]
	v_fmac_f32_e32 v11, v86, v18
	v_pk_fma_f32 v[6:7], v[86:87], v[32:33], v[6:7] op_sel_hi:[0,1,1]
	v_fmac_f32_e32 v11, v88, v19
	v_pk_fma_f32 v[6:7], v[88:89], v[26:27], v[6:7] op_sel_hi:[0,1,1]
	v_fmac_f32_e32 v11, v90, v20
	v_pk_fma_f32 v[6:7], v[90:91], v[34:35], v[6:7] op_sel_hi:[0,1,1]
	v_fmac_f32_e32 v11, v92, v21
	v_pk_fma_f32 v[6:7], v[92:93], v[28:29], v[6:7] op_sel_hi:[0,1,1]
	ds_read_b128 v[14:17], v12
	ds_read_b128 v[18:21], v12 offset:16
	ds_read_b128 v[22:25], v12 offset:4096
	ds_read_b128 v[26:29], v12 offset:4112
	ds_read_b128 v[30:33], v12 offset:8192
	ds_read_b128 v[34:37], v12 offset:8208
	v_add_u32_e32 v12, 32, v12
	s_waitcnt lgkmcnt(3)
	v_mov_b32_e32 v55, v22
	s_waitcnt lgkmcnt(1)
	v_mov_b32_e32 v54, v30
	v_mov_b32_e32 v22, v31
	v_mov_b32_e32 v30, v32
	v_mov_b32_e32 v31, v24
	v_mov_b32_e32 v24, v33
	s_waitcnt lgkmcnt(0)
	v_mov_b32_e32 v32, v34
	v_mov_b32_e32 v33, v26
	v_mov_b32_e32 v26, v35
	v_mov_b32_e32 v34, v36
	v_mov_b32_e32 v35, v28
	v_mov_b32_e32 v28, v37
	s_waitcnt vmcnt(0)
	v_fmac_f32_e32 v11, v94, v14
	v_pk_fma_f32 v[6:7], v[94:95], v[54:55], v[6:7] op_sel_hi:[0,1,1]
	v_fmac_f32_e32 v11, v96, v15
	v_pk_fma_f32 v[6:7], v[96:97], v[22:23], v[6:7] op_sel_hi:[0,1,1]
	v_fmac_f32_e32 v11, v102, v16
	v_pk_fma_f32 v[6:7], v[102:103], v[30:31], v[6:7] op_sel_hi:[0,1,1]
	v_fmac_f32_e32 v11, v104, v17
	v_pk_fma_f32 v[6:7], v[104:105], v[24:25], v[6:7] op_sel_hi:[0,1,1]
	v_fmac_f32_e32 v11, v106, v18
	v_pk_fma_f32 v[6:7], v[106:107], v[32:33], v[6:7] op_sel_hi:[0,1,1]
	v_fmac_f32_e32 v11, v110, v19
	v_pk_fma_f32 v[6:7], v[110:111], v[26:27], v[6:7] op_sel_hi:[0,1,1]
	v_fmac_f32_e32 v11, v114, v20
	v_pk_fma_f32 v[6:7], v[114:115], v[34:35], v[6:7] op_sel_hi:[0,1,1]
	v_fmac_f32_e32 v11, v116, v21
	v_pk_fma_f32 v[6:7], v[116:117], v[28:29], v[6:7] op_sel_hi:[0,1,1]
	ds_write2st64_b32 v2, v11, v7 offset0:48 offset1:49
	ds_write_b32 v2, v6 offset:12800
	s_waitcnt lgkmcnt(0)
	s_barrier
	s_and_saveexec_b64 s[0:1], vcc
	s_cbranch_execz .LBB0_1104
	s_mulk_i32 s5, 0x1800
	s_add_i32 s5, s5, s8
	v_or_b32_e32 v4, s5, v8
	v_readlane_b32 s8, v253, 40
	v_ashrrev_i32_e32 v5, 31, v4
	v_readlane_b32 s12, v253, 44
	v_readlane_b32 s13, v253, 45
	v_add_u32_e32 v16, s5, v3
	v_ashrrev_i32_e32 v17, 31, v16
	v_lshl_add_u64 v[4:5], v[4:5], 2, s[12:13]
	global_load_dword v11, v[4:5], off
	ds_read2st64_b32 v[4:5], v10 offset0:48 offset1:51
	ds_read2st64_b32 v[6:7], v10 offset0:54 offset1:57
	ds_read2st64_b32 v[12:13], v10 offset0:60 offset1:63
	ds_read2st64_b32 v[14:15], v10 offset0:66 offset1:69
	v_readlane_b32 s9, v253, 41
	v_readlane_b32 s10, v253, 42
	v_readlane_b32 s11, v253, 43
	v_readlane_b32 s14, v253, 46
	v_readlane_b32 s15, v253, 47
	v_readlane_b32 s16, v253, 48
	v_readlane_b32 s17, v253, 49
	v_readlane_b32 s18, v253, 50
	v_readlane_b32 s19, v253, 51
	v_readlane_b32 s20, v253, 52
	v_readlane_b32 s21, v253, 53
	v_readlane_b32 s22, v253, 54
	v_readlane_b32 s23, v253, 55
	s_waitcnt vmcnt(0) lgkmcnt(3)
	v_add_f32_e32 v4, v11, v4
	v_add_f32_e32 v4, v4, v5
	s_waitcnt lgkmcnt(2)
	v_add_f32_e32 v4, v4, v6
	v_add_f32_e32 v4, v4, v7
	s_waitcnt lgkmcnt(1)
	v_add_f32_e32 v4, v4, v12
	v_add_f32_e32 v4, v4, v13
	s_waitcnt lgkmcnt(0)
	v_add_f32_e32 v4, v4, v14
	v_add_f32_e32 v6, v4, v15
	v_lshl_add_u64 v[4:5], v[16:17], 2, s[92:93]
	global_store_dword v[4:5], v6, off
	s_branch .LBB0_1104
